# adds batched key loads + nop-free top-k in steady-state PEER selection; selecting waves gather one token (12/4 split) after selecting
# speedup vs baseline: 1.0272x; 1.0185x over previous
_Z11mega_kernel6Params6Inputs:
	s_mov_b32 s100, 0
	s_load_dwordx16 s[4:19], s[0:1], 0x0
	v_readfirstlane_b32 s33, v0
	v_cmp_eq_u32_e32 vcc, 0, v0
	s_waitcnt lgkmcnt(0)
	v_writelane_b32 v254, s4, 0
	s_nop 1
	v_writelane_b32 v254, s5, 1
	v_writelane_b32 v254, s6, 2
	v_writelane_b32 v254, s7, 3
	v_writelane_b32 v254, s8, 4
	v_writelane_b32 v254, s9, 5
	v_writelane_b32 v254, s10, 6
	v_writelane_b32 v254, s11, 7
	v_writelane_b32 v254, s12, 8
	v_writelane_b32 v254, s13, 9
	v_writelane_b32 v254, s14, 10
	v_writelane_b32 v254, s15, 11
	v_writelane_b32 v254, s16, 12
	v_writelane_b32 v254, s17, 13
	v_writelane_b32 v254, s18, 14
	v_writelane_b32 v254, s19, 15
	s_and_saveexec_b64 s[4:5], vcc
	s_cbranch_execz .LBB0_2
	s_add_i32 s3, 0, 0x23fc0
	v_mov_b32_e32 v0, 0
	v_mov_b32_e32 v1, s3
	s_add_i32 s3, 0, 0x23fc4
	ds_write_b32 v1, v0
	v_mov_b32_e32 v1, s3
	s_add_i32 s3, 0, 0x23fc8
	ds_write_b32 v1, v0
	v_mov_b32_e32 v1, s3
	s_add_i32 s3, 0, 0x23fcc
	ds_write_b32 v1, v0
	v_mov_b32_e32 v1, s3
	ds_write_b32 v1, v0

.Lpeer_extra:
	s_mov_b32 s100, 1
	s_lshl_b32 s62, s49, 14
	s_sub_i32 s63, s52, s80
	s_lshl_b32 s63, s63, 4
	s_mov_b32 s61, 4
	s_mov_b32 s101, 15
	s_mov_b64 s[34:35], 0
	v_add_u32_e32 v223, 8, v215
	s_branch .LBB0_732

.LBB0_728:
	s_add_i32 s52, s12, s80
	s_cmpk_lt_i32 s52, 0x300
	s_cselect_b64 s[10:11], -1, 0
	s_cmpk_gt_i32 s52, 0x2ff
	s_cselect_b64 s[26:27], -1, 0
	s_and_b64 s[28:29], s[6:7], s[10:11]
	s_lshl_b32 s53, s49, 14
	s_xor_b64 s[28:29], s[28:29], -1
	s_and_saveexec_b64 s[30:31], s[28:29]
	s_xor_b64 s[28:29], exec, s[30:31]
	s_cbranch_execz .LBB0_803
	s_and_saveexec_b64 s[30:31], s[8:9]
	s_cbranch_execz .LBB0_802
	s_and_b64 s[10:11], s[10:11], exec
	s_cselect_b32 s61, 4, 8
	s_cselect_b32 s101, 11, 15
	s_add_i32 s62, s53, 0
	s_lshl_b32 s63, s12, 4
	s_mov_b64 s[34:35], 0
	v_mov_b32_e32 v223, v215
	s_branch .LBB0_732
.LBB0_731:
	v_add_u32_e32 v223, s61, v223
	v_cmp_lt_i32_e32 vcc, s101, v223
	s_or_b64 s[34:35], vcc, s[34:35]
	s_andn2_b64 exec, exec, s[34:35]
	s_cbranch_execz .LBB0_802

.LBB0_802:
	s_cmp_eq_u32 s100, 1
	s_cbranch_scc0 .Lpeer_normal_exit
	s_mov_b32 s100, 0
	s_mov_b64 exec, -1
	s_branch .LBB0_727

.LBB0_806:
	s_lshr_b32 s10, s30, 1
	v_cndmask_b32_e64 v0, 0, 1, s[12:13]
	s_lshl_b32 s11, s10, 7
	v_lshlrev_b32_e32 v0, 6, v0
	v_or_b32_e32 v0, s11, v0
	v_add_u32_e32 v24, s10, v219
	v_add_u32_e32 v35, v34, v0
	v_lshlrev_b32_e32 v0, 9, v24
	v_lshlrev_b32_e32 v24, 1, v24
	v_mov_b32_e32 v25, v16
	s_and_b32 s10, s30, 1
	v_mov_b32_e32 v1, v16
	v_lshl_add_u64 v[24:25], s[18:19], 0, v[24:25]
	v_lshl_add_u64 v[0:1], v[18:19], 0, v[0:1]
	s_lshl_b32 s82, s10, 8
	v_or_b32_e32 v24, s10, v24
	v_lshl_add_u64 v[0:1], v[0:1], 0, s[82:83]
	v_lshlrev_b64 v[24:25], 15, v[24:25]
	v_lshl_add_u64 v[0:1], v[20:21], 1, v[0:1]
	v_lshl_add_u64 v[24:25], v[22:23], 0, v[24:25]
	s_mov_b32 s31, 0
	s_mov_b32 s98, 0x2000
	s_mov_b32 s99, 0
	global_load_dwordx4 v[12:15], v[0:1], off
	global_load_dwordx4 v[8:11], v[0:1], off offset:64
	global_load_dwordx4 v[4:7], v[0:1], off offset:128
	global_load_dwordx4 v[0:3], v[0:1], off offset:192
	v_lshl_add_u64 v[70:71], v[24:25], 0, s[98:99]
	v_lshl_add_u64 v[72:73], v[70:71], 0, s[98:99]
	v_lshl_add_u64 v[74:75], v[72:73], 0, s[98:99]
	v_lshl_add_u64 v[76:77], v[74:75], 0, s[98:99]
	global_load_dwordx4 v[36:39], v[24:25], off
	global_load_dwordx4 v[78:81], v[24:25], off offset:64
	global_load_dwordx4 v[82:85], v[24:25], off offset:128
	global_load_dwordx4 v[86:89], v[24:25], off offset:192
	global_load_dwordx4 v[40:43], v[70:71], off offset:-4096
	global_load_dwordx4 v[90:93], v[70:71], off offset:-4032
	global_load_dwordx4 v[94:97], v[70:71], off offset:-3968
	global_load_dwordx4 v[98:101], v[70:71], off offset:-3904
	global_load_dwordx4 v[44:47], v[70:71], off
	global_load_dwordx4 v[102:105], v[70:71], off offset:64
	global_load_dwordx4 v[106:109], v[70:71], off offset:128
	global_load_dwordx4 v[110:113], v[70:71], off offset:192
	global_load_dwordx4 v[48:51], v[72:73], off offset:-4096
	global_load_dwordx4 v[114:117], v[72:73], off offset:-4032
	global_load_dwordx4 v[118:121], v[72:73], off offset:-3968
	global_load_dwordx4 v[122:125], v[72:73], off offset:-3904
	global_load_dwordx4 v[52:55], v[72:73], off
	global_load_dwordx4 v[126:129], v[72:73], off offset:64
	global_load_dwordx4 v[130:133], v[72:73], off offset:128
	global_load_dwordx4 v[134:137], v[72:73], off offset:192
	global_load_dwordx4 v[56:59], v[74:75], off offset:-4096
	global_load_dwordx4 v[138:141], v[74:75], off offset:-4032
	global_load_dwordx4 v[142:145], v[74:75], off offset:-3968
	global_load_dwordx4 v[146:149], v[74:75], off offset:-3904
	global_load_dwordx4 v[60:63], v[74:75], off
	global_load_dwordx4 v[150:153], v[74:75], off offset:64
	global_load_dwordx4 v[154:157], v[74:75], off offset:128
	global_load_dwordx4 v[158:161], v[74:75], off offset:192
	global_load_dwordx4 v[162:165], v[76:77], off offset:-4096
	global_load_dwordx4 v[166:169], v[76:77], off offset:-4032
	global_load_dwordx4 v[170:173], v[76:77], off offset:-3968
	global_load_dwordx4 v[174:177], v[76:77], off offset:-3904
	s_waitcnt vmcnt(28)
	v_mfma_f32_16x16x32_bf16 v[36:39], v[12:15], v[36:39], 0
	v_mfma_f32_16x16x32_bf16 v[36:39], v[8:11], v[78:81], v[36:39]
	v_mfma_f32_16x16x32_bf16 v[36:39], v[4:7], v[82:85], v[36:39]
	v_mfma_f32_16x16x32_bf16 v[36:39], v[0:3], v[86:89], v[36:39]
	s_waitcnt vmcnt(24)
	v_mfma_f32_16x16x32_bf16 v[40:43], v[12:15], v[40:43], 0
	v_mfma_f32_16x16x32_bf16 v[40:43], v[8:11], v[90:93], v[40:43]
	v_mfma_f32_16x16x32_bf16 v[40:43], v[4:7], v[94:97], v[40:43]
	v_mfma_f32_16x16x32_bf16 v[40:43], v[0:3], v[98:101], v[40:43]
	s_waitcnt vmcnt(20)
	v_mfma_f32_16x16x32_bf16 v[44:47], v[12:15], v[44:47], 0
	v_mfma_f32_16x16x32_bf16 v[44:47], v[8:11], v[102:105], v[44:47]
	v_mfma_f32_16x16x32_bf16 v[44:47], v[4:7], v[106:109], v[44:47]
	v_mfma_f32_16x16x32_bf16 v[44:47], v[0:3], v[110:113], v[44:47]
	s_waitcnt vmcnt(16)
	v_mfma_f32_16x16x32_bf16 v[48:51], v[12:15], v[48:51], 0
	v_mfma_f32_16x16x32_bf16 v[48:51], v[8:11], v[114:117], v[48:51]
	v_mfma_f32_16x16x32_bf16 v[48:51], v[4:7], v[118:121], v[48:51]
	v_mfma_f32_16x16x32_bf16 v[48:51], v[0:3], v[122:125], v[48:51]
	s_waitcnt vmcnt(12)
	v_mfma_f32_16x16x32_bf16 v[52:55], v[12:15], v[52:55], 0
	v_mfma_f32_16x16x32_bf16 v[52:55], v[8:11], v[126:129], v[52:55]
	v_mfma_f32_16x16x32_bf16 v[52:55], v[4:7], v[130:133], v[52:55]
	v_mfma_f32_16x16x32_bf16 v[52:55], v[0:3], v[134:137], v[52:55]
	s_waitcnt vmcnt(8)
	v_mfma_f32_16x16x32_bf16 v[56:59], v[12:15], v[56:59], 0
	v_mfma_f32_16x16x32_bf16 v[56:59], v[8:11], v[138:141], v[56:59]
	v_mfma_f32_16x16x32_bf16 v[56:59], v[4:7], v[142:145], v[56:59]
	v_mfma_f32_16x16x32_bf16 v[56:59], v[0:3], v[146:149], v[56:59]
	s_waitcnt vmcnt(4)
	v_mfma_f32_16x16x32_bf16 v[60:63], v[12:15], v[60:63], 0
	v_mfma_f32_16x16x32_bf16 v[60:63], v[8:11], v[150:153], v[60:63]
	v_mfma_f32_16x16x32_bf16 v[60:63], v[4:7], v[154:157], v[60:63]
	v_mfma_f32_16x16x32_bf16 v[60:63], v[0:3], v[158:161], v[60:63]
	s_waitcnt vmcnt(0)
	v_mfma_f32_16x16x32_bf16 v[12:15], v[12:15], v[162:165], 0
	v_mfma_f32_16x16x32_bf16 v[8:11], v[8:11], v[166:169], v[12:15]
	v_mfma_f32_16x16x32_bf16 v[4:7], v[4:7], v[170:173], v[8:11]
	v_mfma_f32_16x16x32_bf16 v[0:3], v[0:3], v[174:177], v[4:7]
	v_ashrrev_i32_e32 v68, 31, v36
	v_and_b32_e32 v68, 0x7fffff80, v68
	v_and_b32_e32 v36, 0xffffff80, v36
	v_bitop3_b32 v36, v68, v26, v36 bitop3:0xde
	v_ashrrev_i32_e32 v68, 31, v37
	v_and_b32_e32 v68, 0x7fffff80, v68
	v_and_b32_e32 v37, 0xffffff80, v37
	v_bitop3_b32 v37, v68, v26, v37 bitop3:0xde
	v_ashrrev_i32_e32 v68, 31, v38
	v_and_b32_e32 v68, 0x7fffff80, v68
	v_and_b32_e32 v38, 0xffffff80, v38
	v_bitop3_b32 v38, v68, v26, v38 bitop3:0xde
	v_ashrrev_i32_e32 v68, 31, v39
	v_and_b32_e32 v68, 0x7fffff80, v68
	v_and_b32_e32 v39, 0xffffff80, v39
	v_bitop3_b32 v39, v68, v26, v39 bitop3:0xde
	v_ashrrev_i32_e32 v68, 31, v40
	v_and_b32_e32 v68, 0x7fffff80, v68
	v_and_b32_e32 v40, 0xffffff80, v40
	v_bitop3_b32 v40, v68, v27, v40 bitop3:0xde
	v_ashrrev_i32_e32 v68, 31, v41
	v_and_b32_e32 v68, 0x7fffff80, v68
	v_and_b32_e32 v41, 0xffffff80, v41
	v_bitop3_b32 v41, v68, v27, v41 bitop3:0xde
	v_ashrrev_i32_e32 v68, 31, v42
	v_and_b32_e32 v68, 0x7fffff80, v68
	v_and_b32_e32 v42, 0xffffff80, v42
	v_bitop3_b32 v42, v68, v27, v42 bitop3:0xde
	v_ashrrev_i32_e32 v68, 31, v43
	v_and_b32_e32 v68, 0x7fffff80, v68
	v_and_b32_e32 v43, 0xffffff80, v43
	v_bitop3_b32 v43, v68, v27, v43 bitop3:0xde
	v_ashrrev_i32_e32 v68, 31, v44
	v_and_b32_e32 v68, 0x7fffff80, v68
	v_and_b32_e32 v44, 0xffffff80, v44
	v_bitop3_b32 v44, v68, v28, v44 bitop3:0xde
	v_ashrrev_i32_e32 v68, 31, v45
	v_and_b32_e32 v68, 0x7fffff80, v68
	v_and_b32_e32 v45, 0xffffff80, v45
	v_bitop3_b32 v45, v68, v28, v45 bitop3:0xde
	v_ashrrev_i32_e32 v68, 31, v46
	v_and_b32_e32 v68, 0x7fffff80, v68
	v_and_b32_e32 v46, 0xffffff80, v46
	v_bitop3_b32 v46, v68, v28, v46 bitop3:0xde
	v_ashrrev_i32_e32 v68, 31, v47
	v_and_b32_e32 v68, 0x7fffff80, v68
	v_and_b32_e32 v47, 0xffffff80, v47
	v_bitop3_b32 v47, v68, v28, v47 bitop3:0xde
	v_ashrrev_i32_e32 v68, 31, v48
	v_and_b32_e32 v68, 0x7fffff80, v68
	v_and_b32_e32 v48, 0xffffff80, v48
	v_bitop3_b32 v48, v68, v29, v48 bitop3:0xde
	v_ashrrev_i32_e32 v68, 31, v49
	v_and_b32_e32 v68, 0x7fffff80, v68
	v_and_b32_e32 v49, 0xffffff80, v49
	v_bitop3_b32 v49, v68, v29, v49 bitop3:0xde
	v_ashrrev_i32_e32 v68, 31, v50
	v_and_b32_e32 v68, 0x7fffff80, v68
	v_and_b32_e32 v50, 0xffffff80, v50
	v_bitop3_b32 v50, v68, v29, v50 bitop3:0xde
	v_ashrrev_i32_e32 v68, 31, v51
	v_and_b32_e32 v68, 0x7fffff80, v68
	v_and_b32_e32 v51, 0xffffff80, v51
	v_bitop3_b32 v51, v68, v29, v51 bitop3:0xde
	v_ashrrev_i32_e32 v68, 31, v52
	v_and_b32_e32 v68, 0x7fffff80, v68
	v_and_b32_e32 v52, 0xffffff80, v52
	v_bitop3_b32 v52, v68, v30, v52 bitop3:0xde
	v_ashrrev_i32_e32 v68, 31, v53
	v_and_b32_e32 v68, 0x7fffff80, v68
	v_and_b32_e32 v53, 0xffffff80, v53
	v_bitop3_b32 v53, v68, v30, v53 bitop3:0xde
	v_ashrrev_i32_e32 v68, 31, v54
	v_and_b32_e32 v68, 0x7fffff80, v68
	v_and_b32_e32 v54, 0xffffff80, v54
	v_bitop3_b32 v54, v68, v30, v54 bitop3:0xde
	v_ashrrev_i32_e32 v68, 31, v55
	v_and_b32_e32 v68, 0x7fffff80, v68
	v_and_b32_e32 v55, 0xffffff80, v55
	v_bitop3_b32 v55, v68, v30, v55 bitop3:0xde
	v_ashrrev_i32_e32 v68, 31, v56
	v_and_b32_e32 v68, 0x7fffff80, v68
	v_and_b32_e32 v56, 0xffffff80, v56
	v_bitop3_b32 v56, v68, v31, v56 bitop3:0xde
	v_ashrrev_i32_e32 v68, 31, v57
	v_and_b32_e32 v68, 0x7fffff80, v68
	v_and_b32_e32 v57, 0xffffff80, v57
	v_bitop3_b32 v57, v68, v31, v57 bitop3:0xde
	v_ashrrev_i32_e32 v68, 31, v58
	v_and_b32_e32 v68, 0x7fffff80, v68
	v_and_b32_e32 v58, 0xffffff80, v58
	v_bitop3_b32 v58, v68, v31, v58 bitop3:0xde
	v_ashrrev_i32_e32 v68, 31, v59
	v_and_b32_e32 v68, 0x7fffff80, v68
	v_and_b32_e32 v59, 0xffffff80, v59
	v_bitop3_b32 v59, v68, v31, v59 bitop3:0xde
	v_ashrrev_i32_e32 v68, 31, v60
	v_and_b32_e32 v68, 0x7fffff80, v68
	v_and_b32_e32 v60, 0xffffff80, v60
	v_bitop3_b32 v60, v68, v32, v60 bitop3:0xde
	v_ashrrev_i32_e32 v68, 31, v61
	v_and_b32_e32 v68, 0x7fffff80, v68
	v_and_b32_e32 v61, 0xffffff80, v61
	v_bitop3_b32 v61, v68, v32, v61 bitop3:0xde
	v_ashrrev_i32_e32 v68, 31, v62
	v_and_b32_e32 v68, 0x7fffff80, v68
	v_and_b32_e32 v62, 0xffffff80, v62
	v_bitop3_b32 v62, v68, v32, v62 bitop3:0xde
	v_ashrrev_i32_e32 v68, 31, v63
	v_and_b32_e32 v68, 0x7fffff80, v68
	v_and_b32_e32 v63, 0xffffff80, v63
	v_bitop3_b32 v63, v68, v32, v63 bitop3:0xde
	v_ashrrev_i32_e32 v4, 31, v0
	v_and_b32_e32 v4, 0x7fffff80, v4
	v_and_b32_e32 v0, 0xffffff80, v0
	v_bitop3_b32 v0, v4, v33, v0 bitop3:0xde
	v_ashrrev_i32_e32 v4, 31, v1
	v_and_b32_e32 v4, 0x7fffff80, v4
	v_and_b32_e32 v1, 0xffffff80, v1
	v_bitop3_b32 v1, v4, v33, v1 bitop3:0xde
	v_ashrrev_i32_e32 v4, 31, v2
	v_and_b32_e32 v4, 0x7fffff80, v4
	v_and_b32_e32 v2, 0xffffff80, v2
	v_bitop3_b32 v2, v4, v33, v2 bitop3:0xde
	v_ashrrev_i32_e32 v4, 31, v3
	v_and_b32_e32 v4, 0x7fffff80, v4
	v_and_b32_e32 v3, 0xffffff80, v3
	v_bitop3_b32 v3, v4, v33, v3 bitop3:0xde
	s_branch .LBB0_808
.LBB0_807:
	s_or_b64 exec, exec, s[10:11]
	s_add_i32 s31, s31, 4
	v_cmp_ne_u32_e64 s[10:11], v39, v8
	v_cmp_ne_u32_e64 s[98:99], v43, v8
	v_cmp_ne_u32_e64 s[100:101], v47, v8
	v_cndmask_b32_e64 v39, v195, v39, s[10:11]
	v_cndmask_b32_e64 v43, v195, v43, s[98:99]
	v_cndmask_b32_e64 v47, v195, v47, s[100:101]
	v_cmp_ne_u32_e64 s[10:11], v51, v8
	v_cmp_ne_u32_e64 s[98:99], v55, v8
	v_cmp_ne_u32_e64 s[100:101], v59, v8
	v_cndmask_b32_e64 v51, v195, v51, s[10:11]
	v_cndmask_b32_e64 v55, v195, v55, s[98:99]
	v_cndmask_b32_e64 v59, v195, v59, s[100:101]
	v_cmp_ne_u32_e64 s[10:11], v63, v8
	v_cmp_ne_u32_e64 s[98:99], v3, v8
	v_cmp_ne_u32_e64 s[100:101], v38, v7
	v_cndmask_b32_e64 v63, v195, v63, s[10:11]
	v_cndmask_b32_e64 v3, v195, v3, s[98:99]
	v_cndmask_b32_e64 v38, v195, v38, s[100:101]
	v_cmp_ne_u32_e64 s[10:11], v42, v7
	v_cmp_ne_u32_e64 s[98:99], v46, v7
	v_cmp_ne_u32_e64 s[100:101], v50, v7
	v_cndmask_b32_e64 v42, v195, v42, s[10:11]
	v_cndmask_b32_e64 v46, v195, v46, s[98:99]
	v_cndmask_b32_e64 v50, v195, v50, s[100:101]
	v_cmp_ne_u32_e64 s[10:11], v54, v7
	v_cmp_ne_u32_e64 s[98:99], v58, v7
	v_cmp_ne_u32_e64 s[100:101], v62, v7
	v_cndmask_b32_e64 v54, v195, v54, s[10:11]
	v_cndmask_b32_e64 v58, v195, v58, s[98:99]
	v_cndmask_b32_e64 v62, v195, v62, s[100:101]
	v_cmp_ne_u32_e64 s[10:11], v2, v7
	v_cmp_ne_u32_e64 s[98:99], v37, v5
	v_cmp_ne_u32_e64 s[100:101], v41, v5
	v_cndmask_b32_e64 v2, v195, v2, s[10:11]
	v_cndmask_b32_e64 v37, v195, v37, s[98:99]
	v_cndmask_b32_e64 v41, v195, v41, s[100:101]
	v_cmp_ne_u32_e64 s[10:11], v45, v5
	v_cmp_ne_u32_e64 s[98:99], v49, v5
	v_cmp_ne_u32_e64 s[100:101], v53, v5
	v_cndmask_b32_e64 v45, v195, v45, s[10:11]
	v_cndmask_b32_e64 v49, v195, v49, s[98:99]
	v_cndmask_b32_e64 v53, v195, v53, s[100:101]
	v_cmp_ne_u32_e64 s[10:11], v57, v5
	v_cmp_ne_u32_e64 s[98:99], v61, v5
	v_cmp_ne_u32_e64 s[100:101], v1, v5
	v_cndmask_b32_e64 v57, v195, v57, s[10:11]
	v_cndmask_b32_e64 v61, v195, v61, s[98:99]
	v_cndmask_b32_e64 v1, v195, v1, s[100:101]
	v_cmp_ne_u32_e64 s[10:11], v36, v4
	v_cmp_ne_u32_e64 s[98:99], v40, v4
	v_cmp_ne_u32_e64 s[100:101], v44, v4
	v_cndmask_b32_e64 v36, v195, v36, s[10:11]
	v_cndmask_b32_e64 v40, v195, v40, s[98:99]
	v_cndmask_b32_e64 v44, v195, v44, s[100:101]
	v_cmp_ne_u32_e64 s[10:11], v48, v4
	v_cmp_ne_u32_e64 s[98:99], v52, v4
	v_cmp_ne_u32_e64 s[100:101], v56, v4
	v_cndmask_b32_e64 v48, v195, v48, s[10:11]
	v_cndmask_b32_e64 v52, v195, v52, s[98:99]
	v_cndmask_b32_e64 v56, v195, v56, s[100:101]
	v_cmp_ne_u32_e64 s[10:11], v60, v4
	v_cmp_ne_u32_e64 s[98:99], v0, v4
	s_nop 0
	v_cndmask_b32_e64 v60, v195, v60, s[10:11]
	v_cndmask_b32_e64 v0, v195, v0, s[98:99]
	s_cmp_lg_u32 s31, 64
	s_cbranch_scc0 .LBB0_805
.LBB0_808:
	v_max3_i32 v4, v36, v40, v44
	v_max3_i32 v5, v37, v41, v45
	v_max3_i32 v7, v38, v42, v46
	v_max3_i32 v8, v39, v43, v47
	v_max3_i32 v4, v4, v48, v52
	v_max3_i32 v5, v5, v49, v53
	v_max3_i32 v7, v7, v50, v54
	v_max3_i32 v8, v8, v51, v55
	v_max3_i32 v4, v4, v56, v60
	v_max3_i32 v5, v5, v57, v61
	v_max3_i32 v7, v7, v58, v62
	v_max3_i32 v8, v8, v59, v63
	v_max_i32_e32 v4, v4, v0
	v_max_i32_e32 v5, v5, v1
	v_max_i32_e32 v7, v7, v2
	v_max_i32_e32 v8, v8, v3
	v_max_i32_dpp v4, v4, v4 quad_perm:[1,0,3,2] row_mask:0xf bank_mask:0xf bound_ctrl:1
	v_max_i32_dpp v5, v5, v5 quad_perm:[1,0,3,2] row_mask:0xf bank_mask:0xf bound_ctrl:1
	v_max_i32_dpp v7, v7, v7 quad_perm:[1,0,3,2] row_mask:0xf bank_mask:0xf bound_ctrl:1
	v_max_i32_dpp v8, v8, v8 quad_perm:[1,0,3,2] row_mask:0xf bank_mask:0xf bound_ctrl:1
	v_max_i32_dpp v4, v4, v4 quad_perm:[2,3,0,1] row_mask:0xf bank_mask:0xf bound_ctrl:1
	v_max_i32_dpp v5, v5, v5 quad_perm:[2,3,0,1] row_mask:0xf bank_mask:0xf bound_ctrl:1
	v_max_i32_dpp v7, v7, v7 quad_perm:[2,3,0,1] row_mask:0xf bank_mask:0xf bound_ctrl:1
	v_max_i32_dpp v8, v8, v8 quad_perm:[2,3,0,1] row_mask:0xf bank_mask:0xf bound_ctrl:1
	v_max_i32_dpp v4, v4, v4 row_half_mirror row_mask:0xf bank_mask:0xf bound_ctrl:1
	v_max_i32_dpp v5, v5, v5 row_half_mirror row_mask:0xf bank_mask:0xf bound_ctrl:1
	v_max_i32_dpp v7, v7, v7 row_half_mirror row_mask:0xf bank_mask:0xf bound_ctrl:1
	v_max_i32_dpp v8, v8, v8 row_half_mirror row_mask:0xf bank_mask:0xf bound_ctrl:1
	v_max_i32_dpp v4, v4, v4 row_mirror row_mask:0xf bank_mask:0xf bound_ctrl:1
	v_max_i32_dpp v5, v5, v5 row_mirror row_mask:0xf bank_mask:0xf bound_ctrl:1
	v_max_i32_dpp v7, v7, v7 row_mirror row_mask:0xf bank_mask:0xf bound_ctrl:1
	v_max_i32_dpp v8, v8, v8 row_mirror row_mask:0xf bank_mask:0xf bound_ctrl:1
	v_add_u32_e32 v6, s31, v35
	s_and_saveexec_b64 s[10:11], vcc
	s_cbranch_execz .LBB0_807
	v_and_b32_e32 v64, 0xffffff80, v4
	v_ashrrev_i32_e32 v65, 31, v4
	v_bitop3_b32 v64, v65, v64, s81 bitop3:0x6c
	v_bitop3_b32 v65, v4, s58, v4 bitop3:0xc
	ds_write2st64_b32 v6, v64, v65 offset1:32
	v_and_b32_e32 v66, 0xffffff80, v5
	v_ashrrev_i32_e32 v67, 31, v5
	v_bitop3_b32 v66, v67, v66, s81 bitop3:0x6c
	v_bitop3_b32 v67, v5, s58, v5 bitop3:0xc
	ds_write2st64_b32 v6, v66, v67 offset0:2 offset1:34
	v_and_b32_e32 v68, 0xffffff80, v7
	v_ashrrev_i32_e32 v69, 31, v7
	v_bitop3_b32 v68, v69, v68, s81 bitop3:0x6c
	v_bitop3_b32 v69, v7, s58, v7 bitop3:0xc
	ds_write2st64_b32 v6, v68, v69 offset0:4 offset1:36
	v_and_b32_e32 v70, 0xffffff80, v8
	v_ashrrev_i32_e32 v71, 31, v8
	v_bitop3_b32 v70, v71, v70, s81 bitop3:0x6c
	v_bitop3_b32 v71, v8, s58, v8 bitop3:0xc
	ds_write2st64_b32 v6, v70, v71 offset0:6 offset1:38
	s_branch .LBB0_807
